# phase 0 iterates a compacted task index (deferred transposition ranges removed): <=4 tasks per block
# speedup vs baseline: 1.0125x; 1.0020x over previous
.LBB0_18:
	s_or_b64 exec, exec, s[4:5]
	s_cmpk_gt_i32 s69, 0xe90
	v_lshlrev_b32_e32 v144, 4, v146
	v_lshrrev_b32_e32 v157, 4, v146
	v_lshlrev_b32_e32 v155, 2, v146
	v_lshrrev_b32_e32 v149, 3, v146
	v_and_b32_e32 v151, 7, v146
	v_lshlrev_b32_e32 v152, 3, v146
	v_and_b32_e32 v148, 15, v146
	s_cbranch_scc1 .LBB0_144
	v_lshlrev_b32_e32 v2, 1, v146
	v_and_b32_e32 v0, 32, v152
	v_and_b32_e32 v2, 4, v2
	v_and_b32_e32 v3, 16, v144
	v_or3_b32 v38, v0, v2, v3
	v_cvt_f32_ubyte0_e32 v2, v148
	v_mul_f32_e32 v18, 0xbd800000, v2
	v_mov_b32_e32 v2, 0x461c4000
	v_cmp_eq_f32_e32 vcc, 0, v18
	s_movk_i32 s0, 0xa0
	v_cmp_gt_u32_e64 s[4:5], s0, v146
	v_cndmask_b32_e64 v12, v2, 1.0, vcc
	v_frexp_mant_f32_e32 v2, v12
	s_mov_b32 s0, 0x3f2aaaab
	v_cmp_gt_f32_e64 s[6:7], s0, v2
	s_mov_b32 s0, 0x3f317218
	s_movk_i32 s2, 0x204
	v_cndmask_b32_e64 v3, 1.0, 2.0, s[6:7]
	v_mul_f32_e32 v2, v2, v3
	v_add_f32_e32 v5, 1.0, v2
	v_rcp_f32_e32 v10, v5
	v_add_f32_e32 v3, -1.0, v5
	v_sub_f32_e32 v7, v2, v3
	v_add_f32_e32 v3, -1.0, v2
	v_mul_f32_e32 v11, v3, v10
	v_mul_f32_e32 v4, v5, v11
	v_fma_f32 v6, v11, v5, -v4
	v_fmac_f32_e32 v6, v11, v7
	v_add_f32_e32 v2, v4, v6
	v_sub_f32_e32 v5, v3, v2
	v_pk_add_f32 v[8:9], v[2:3], v[4:5] neg_lo:[0,1] neg_hi:[0,1]
	v_mov_b32_e32 v7, v2
	v_pk_add_f32 v[2:3], v[8:9], v[6:7] neg_lo:[0,1] neg_hi:[0,1]
	v_mov_b32_e32 v6, 0x3e91f4c4
	v_add_f32_e32 v2, v2, v3
	v_add_f32_e32 v2, v5, v2
	v_mul_f32_e32 v3, v10, v2
	v_add_f32_e32 v2, v11, v3
	v_sub_f32_e32 v4, v2, v11
	v_sub_f32_e32 v13, v3, v4
	v_mul_f32_e32 v3, v2, v2
	v_fma_f32 v5, v2, v2, -v3
	v_add_f32_e32 v4, v13, v13
	v_fmac_f32_e32 v5, v2, v4
	v_add_f32_e32 v4, v3, v5
	v_fmac_f32_e32 v6, 0x3e76c4e1, v4
	v_fmaak_f32 v6, v4, v6, 0x3ecccdef
	v_sub_f32_e32 v3, v4, v3
	v_sub_f32_e32 v14, v5, v3
	v_mul_f32_e32 v3, v4, v6
	v_fma_f32 v5, v4, v6, -v3
	v_fmac_f32_e32 v5, v14, v6
	v_add_f32_e32 v6, v3, v5
	v_add_f32_e32 v7, 0x3f2aaaaa, v6
	v_sub_f32_e32 v3, v6, v3
	v_sub_f32_e32 v3, v5, v3
	v_add_f32_e32 v5, 0xbf2aaaaa, v7
	v_add_f32_e32 v3, 0x31739010, v3
	v_sub_f32_e32 v5, v6, v5
	v_pk_mul_f32 v[8:9], v[2:3], v[4:5]
	v_pk_add_f32 v[10:11], v[2:3], v[4:5]
	v_fma_f32 v6, v4, v2, -v8
	v_fmac_f32_e32 v6, v4, v13
	v_mov_b32_e32 v9, v11
	v_fmac_f32_e32 v6, v14, v2
	v_pk_add_f32 v[4:5], v[8:9], v[6:7]
	v_ldexp_f32 v14, v13, 1
	v_sub_f32_e32 v3, v4, v8
	v_sub_f32_e32 v3, v6, v3
	v_sub_f32_e32 v6, v7, v5
	v_add_f32_e32 v9, v11, v6
	v_pk_mul_f32 v[6:7], v[4:5], v[4:5] op_sel:[0,1] op_sel_hi:[1,0]
	v_cvt_f64_f32_e32 v[10:11], v12
	v_frexp_exp_i32_f64_e32 v7, v[10:11]
	v_subbrev_co_u32_e64 v7, s[6:7], 0, v7, s[6:7]
	v_cvt_f32_i32_e32 v7, v7
	v_fma_f32 v8, v4, v5, -v6
	v_fmac_f32_e32 v8, v4, v9
	v_fmac_f32_e32 v8, v3, v5
	v_mul_f32_e32 v4, 0x3f317218, v7
	v_fma_f32 v3, v7, s0, -v4
	v_fmamk_f32 v10, v7, 0xb102e308, v3
	v_ldexp_f32 v11, v2, 1
	v_add_f32_e32 v5, v6, v8
	v_pk_add_f32 v[2:3], v[4:5], v[10:11]
	v_mov_b32_e32 v12, v5
	v_mov_b32_e32 v13, v3
	v_mov_b32_e32 v7, v11
	v_pk_add_f32 v[6:7], v[12:13], v[6:7] neg_lo:[0,1] neg_hi:[0,1]
	v_mov_b32_e32 v9, v5
	v_pk_add_f32 v[6:7], v[8:9], v[6:7] neg_lo:[0,1] neg_hi:[0,1]
	v_mov_b32_e32 v11, v2
	v_add_f32_e32 v5, v14, v6
	v_add_f32_e32 v5, v5, v7
	v_pk_add_f32 v[6:7], v[2:3], v[4:5] neg_lo:[0,1] neg_hi:[0,1]
	v_pk_add_f32 v[8:9], v[2:3], v[4:5]
	v_mov_b32_e32 v4, v5
	v_mov_b32_e32 v7, v9
	v_pk_add_f32 v[12:13], v[10:11], v[6:7] neg_lo:[0,1] neg_hi:[0,1]
	v_pk_add_f32 v[6:7], v[10:11], v[6:7]
	v_mov_b32_e32 v5, v2
	v_pk_add_f32 v[10:11], v[6:7], v[2:3] op_sel:[1,0] op_sel_hi:[0,1] neg_lo:[0,1] neg_hi:[0,1]
	v_pk_add_f32 v[14:15], v[8:9], v[10:11] op_sel_hi:[1,0] neg_lo:[0,1] neg_hi:[0,1]
	v_mov_b32_e32 v8, v9
	v_mov_b32_e32 v9, v7
	v_pk_mov_b32 v[10:11], v[2:3], v[10:11] op_sel:[1,0]
	v_mov_b32_e32 v14, v12
	v_pk_add_f32 v[8:9], v[8:9], v[10:11] neg_lo:[0,1] neg_hi:[0,1]
	v_mov_b32_e32 v13, v7
	v_pk_add_f32 v[2:3], v[4:5], v[8:9] neg_lo:[0,1] neg_hi:[0,1]
	s_mov_b32 s3, 0x42b17218
	v_pk_add_f32 v[4:5], v[14:15], v[2:3]
	s_mov_b32 s60, 0x3fb8aa3b
	v_pk_add_f32 v[8:9], v[4:5], v[4:5] op_sel:[0,1] op_sel_hi:[1,0]
	v_readlane_b32 s16, v253, 0
	v_pk_add_f32 v[6:7], v[6:7], v[8:9] op_sel:[1,0] op_sel_hi:[0,1]
	v_mov_b32_e32 v5, v6
	v_pk_add_f32 v[10:11], v[4:5], v[12:13] neg_lo:[0,1] neg_hi:[0,1]
	v_mov_b32_e32 v3, v8
	v_sub_f32_e32 v4, v4, v10
	v_pk_add_f32 v[2:3], v[2:3], v[10:11] neg_lo:[0,1] neg_hi:[0,1]
	v_sub_f32_e32 v4, v12, v4
	v_add_f32_e32 v2, v2, v4
	v_add_f32_e32 v2, v2, v3
	v_add_f32_e32 v3, v6, v2
	v_sub_f32_e32 v4, v3, v6
	v_sub_f32_e32 v2, v2, v4
	v_mul_f32_e32 v4, v18, v3
	v_fma_f32 v3, v18, v3, -v4
	v_fmac_f32_e32 v3, v18, v2
	v_add_f32_e32 v2, v4, v3
	v_cmp_class_f32_e64 s[6:7], v4, s2
	v_sub_f32_e32 v5, v2, v4
	v_sub_f32_e32 v3, v3, v5
	v_cndmask_b32_e64 v2, v2, v4, s[6:7]
	v_mov_b32_e32 v4, 0x37000000
	v_cmp_eq_f32_e64 s[6:7], s3, v2
	v_readlane_b32 s17, v253, 1
	s_load_dwordx2 s[40:41], s[16:17], 0x160
	v_cndmask_b32_e64 v4, 0, v4, s[6:7]
	v_sub_f32_e32 v5, v2, v4
	v_mul_f32_e32 v6, 0x3fb8aa3b, v5
	v_fma_f32 v7, v5, s60, -v6
	v_rndne_f32_e32 v8, v6
	v_fmac_f32_e32 v7, 0x32a5705f, v5
	v_sub_f32_e32 v6, v6, v8
	v_add_f32_e32 v6, v6, v7
	v_exp_f32_e32 v6, v6
	v_cvt_i32_f32_e32 v7, v8
	s_mov_b32 s0, 0x7f800000
	v_cmp_neq_f32_e64 s[6:7], |v2|, s0
	s_mov_b32 s61, 0xc2ce8ed0
	s_add_u32 s34, s16, 24
	v_cndmask_b32_e64 v2, 0, v3, s[6:7]
	v_ldexp_f32 v3, v6, v7
	v_cmp_ngt_f32_e64 s[6:7], s61, v5
	s_addc_u32 s35, s17, 0
	v_mov_b32_e32 v53, 0x7f800000
	v_cndmask_b32_e64 v3, 0, v3, s[6:7]
	v_cmp_nlt_f32_e64 s[6:7], s3, v5
	v_add_f32_e32 v2, v4, v2
	s_waitcnt lgkmcnt(0)
	s_add_u32 s42, s40, 0xf67e000
	v_cndmask_b32_e64 v3, v53, v3, s[6:7]
	v_fma_f32 v2, v3, v2, v3
	v_cmp_class_f32_e64 s[6:7], v3, s2
	v_cmp_neq_f32_e64 s[0:1], v18, |v18|
	s_addc_u32 s43, s41, 0
	v_cndmask_b32_e64 v2, v2, v3, s[6:7]
	v_cndmask_b32_e64 v3, v53, 0, s[0:1]
	s_add_u32 s62, s40, 0x8c40000
	v_cndmask_b32_e64 v3, v3, 1.0, vcc
	v_cmp_class_f32_e64 s[0:1], v18, s2
	s_addc_u32 s63, s41, 0
	s_add_u32 s44, s40, 0x8740000
	v_cndmask_b32_e64 v54, |v2|, v3, s[0:1]
	v_lshlrev_b32_e32 v2, 2, v149
	s_movk_i32 s0, 0x820
	v_mad_u32_u24 v55, v151, s0, v2
	s_addc_u32 s45, s41, 0
	v_xor_b32_e32 v2, 0x1300, v146
	s_add_u32 s46, s40, 0x7f00000
	v_lshrrev_b32_e32 v2, 8, v2
	s_addc_u32 s47, s41, 0
	v_add_u32_e32 v7, 1, v2
	v_lshrrev_b32_e32 v2, 8, v146
	s_add_u32 s48, s40, 0x7700000
	v_sub_u32_e32 v2, 32, v2
	v_and_b32_e32 v3, 22, v7
	v_mov_b32_e32 v35, 0
	s_addc_u32 s49, s41, 0
	v_add_u32_e32 v8, -2, v3
	v_and_b32_e32 v57, 62, v2
	s_add_u32 s50, s40, 0x7200000
	s_load_dwordx4 s[28:31], s[16:17], 0x48
	v_lshl_add_u32 v9, v57, 8, v146
	v_cmp_ne_u32_e64 s[6:7], v2, v57
	v_and_b32_e32 v2, 2, v8
	v_mov_b32_e32 v153, v35
	s_addc_u32 s51, s41, 0
	v_lshl_add_u32 v58, v3, 8, v146
	v_cmp_eq_u32_e64 s[10:11], 0, v2
	v_cmp_ne_u32_e64 s[12:13], v7, v3
	v_lshl_add_u64 v[2:3], s[40:41], 0, v[152:153]
	s_mov_b64 s[14:15], 0xf67c000
	v_lshlrev_b32_e32 v34, 4, v9
	s_load_dwordx8 s[20:27], s[16:17], 0xb0
	s_add_u32 s52, s40, 0xf440000
	s_mov_b64 s[0:1], 0xfa82100
	v_lshl_add_u64 v[42:43], v[2:3], 0, s[14:15]
	v_lshl_add_u64 v[2:3], s[40:41], 0, v[34:35]
	v_and_b32_e32 v37, 60, v155
	v_and_b32_e32 v39, 28, v155
	v_lshrrev_b32_e32 v40, 5, v146
	v_and_b32_e32 v52, 31, v146
	s_addc_u32 s53, s41, 0
	v_lshl_add_u64 v[44:45], v[2:3], 0, s[0:1]
	v_lshlrev_b32_e32 v2, 10, v7
	v_lshlrev_b32_e32 v1, 2, v37
	v_mul_u32_u24_e32 v0, 0x18000, v149
	v_lshlrev_b32_e32 v16, 2, v39
	v_lshlrev_b32_e32 v17, 2, v52
	v_mul_u32_u24_e32 v4, 0x104, v157
	v_mul_u32_u24_e32 v5, 0x280, v149
	v_lshlrev_b32_e32 v6, 7, v40
	s_add_u32 s54, s40, 0xfa82100
	v_and_b32_e32 v2, 0x5800, v2
	v_mov_b32_e32 v145, v35
	v_lshlrev_b32_e32 v36, 3, v151
	v_lshlrev_b32_e32 v41, 7, v149
	v_add_u32_e32 v56, 32, v149
	s_addc_u32 s55, s41, 0
	v_add_u32_e32 v147, 0x100, v146
	s_waitcnt lgkmcnt(0)
	s_mov_b32 s64, s30
	s_mov_b32 s65, s31
	s_mov_b32 s66, s30
	s_mov_b32 s67, s31
	s_mov_b32 s70, s28
	s_mov_b32 s71, s29
	s_mov_b32 s78, s28
	s_mov_b32 s79, s29
	v_cmp_ne_u32_e64 s[8:9], 0, v8
	v_add_u32_e32 v59, 0xffffff00, v146
	v_add_u32_e32 v60, 0xffffff00, v9
	v_and_b32_e32 v61, 20, v7
	v_add_u32_e32 v62, v2, v155
	s_mov_b32 s80, 0xfe5163ab
	s_mov_b32 s81, 0x3c439041
	s_mov_b32 s82, 0xdb629599
	s_mov_b32 s83, 0xf534ddc0
	s_mov_b32 s84, 0xfc2757d1
	s_mov_b32 s85, 0x4e441529
	s_mov_b32 s86, 0xa2f9836e
	s_mov_b32 s87, 0x3fc90fda
	s_mov_b32 s88, 0xbfc90fda
	v_mov_b32_e32 v63, 0x3c0881c4
	v_mov_b32_e32 v64, 0xbab64f3b
	v_mov_b32_e32 v33, 0x3eb60549
	s_movk_i32 s89, 0x400
	v_add_u32_e32 v65, v1, v4
	s_mov_b32 s90, 0xbfb8aa3b
	s_mov_b32 s91, 0x42ce8ed0
	s_mov_b32 s92, 0xc2b17218
	v_lshlrev_b32_e32 v46, 2, v0
	s_mov_b32 s93, 0x27000
	s_mov_b32 s94, 0x2a000
	s_mov_b32 s95, 0x2d000
	v_add_u32_e32 v66, v16, v5
	v_add_u32_e32 v67, v17, v6
	s_movk_i32 s96, 0xc00
	v_not_b32_e32 v68, 63
	v_not_b32_e32 v69, 31
	v_mov_b32_e32 v70, 0x7fc00000
	v_mov_b32_e32 v72, v35
	v_mov_b32_e32 v73, v35
	v_mov_b32_e32 v74, v35
	v_mov_b32_e32 v75, v35
	s_mov_b32 s97, s69
	s_mov_b32 s98, s69
	s_mov_b32 s36, 0
	s_branch .LBB0_22

.LBB0_21:
	v_readlane_b32 s14, v253, 0
	v_readlane_b32 s15, v253, 1
	s_load_dwordx2 s[0:1], s[14:15], 0x168
	s_waitcnt lgkmcnt(0)
	s_add_i32 s98, s98, s0
	s_cmp_lt_u32 s98, 0x2c0
	s_cselect_b32 s1, 0, 0x550
	s_cmp_lt_u32 s98, 0x340
	s_cselect_b32 s1, s1, 0x6d0
	s_add_u32 s97, s98, s1
	s_cmpk_lt_i32 s97, 0xe91
	s_cbranch_scc0 .LBB0_144
